# v32 + nt hint on the scan output (y) stores
# baseline (speedup 1.0000x reference)
; __device__ __forceinline__ void scan_unit(const Params& p, int unit) {
;     ...
;         auto commit = [&](int bufi) {
;             float* buf = (float*)(smem + bufi * SC_BUF);
;             float f[5][8];
; #pragma unroll
;             for (int a = 0; a < 5; ++a) {
;                 const h16x8 hv = __builtin_bit_cast(h16x8, rg[a]);
; #pragma unroll
;                 for (int e = 0; e < 8; ++e) f[a][e] = (float)hv[e];
;             }
;             const bool odd = (i >> 3) & 1;
;             float ckk = 0.f, cbk = 0.f;
;             {
;                 const h16x8 pw = __builtin_bit_cast(h16x8, rp[0]), pk = __builtin_bit_cast(h16x8, rp[1]), pb = __builtin_bit_cast(h16x8, rp[2]);
; #pragma unroll
;                 for (int e = 0; e < 8; ++e) {
;                     const float kk2 = f[3][e];
;                     ckk += (float)pk[e] * kk2; cbk += (float)pb[e] * kk2;
;                     if (odd) f[3][e] = (1.0f - (float)pw[e]) * kk2;
;                 }
;             }
;             ckk += dppf<0xB1>(ckk); cbk += dppf<0xB1>(cbk); ckk += dppf<0x4E>(ckk); cbk += dppf<0x4E>(cbk); ckk += dppf<0x141>(ckk); cbk += dppf<0x141>(cbk);
; #pragma unroll
;             for (int a = 0; a < 5; ++a) {
;                 f32x4 lo, hi;
; #pragma unroll
;                 for (int e = 0; e < 4; ++e) { lo[e] = f[a][e]; hi[e] = f[a][4 + e]; }
;                 if (a == 1) { lo = 1.0f - lo; hi = 1.0f - hi; }
;                 if (a == 4) { lo = -lo; hi = -hi; }
;                 *(f32x4*)(buf + a * SC_ARR + i * 8) = lo; *(f32x4*)(buf + a * SC_ARR + i * 8 + 4) = hi;
;             }
;             const h16x2 v2 = __builtin_bit_cast(h16x2, rv);
;             f32x2 vf; vf[0] = (float)v2[0]; vf[1] = (float)v2[1];
;             *(f32x2*)(buf + SC_VOFF + (i >> 3) * 16 + (i & 7) * 2) = vf;
;             if (odd && (i & 7) == 0) { f32x2 cf; cf[0] = ckk; cf[1] = cbk; *(f32x2*)(buf + SC_COFF + (i >> 4) * 2) = cf; }
;         };
;         auto yout = [&](int c) {
;             const float* yb = (const float*)(smem + SC_YOFF + (c & 1) * SC_YBUF);
;             const f32x2 v = *(const f32x2*)(yb + (i >> 3) * 16 + (i & 7) * 2);
;             *(unsigned*)(Y + hb + (size_t)(c * SC_TC + (i >> 3)) * 64 + vr0 + (i & 7) * 2) = pk_bf16(v[0], v[1]);
;         };
.LBB0_797:
	s_and_b32 s4, s11, 0x800
	v_add_u32_e32 v33, s4, v54
	ds_read_b64 v[34:35], v33
	v_lshl_add_u64 v[58:59], s[90:91], 0, v[38:39]
	s_waitcnt vmcnt(8)
	v_cvt_f32_f16_sdwa v57, v28 dst_sel:DWORD dst_unused:UNUSED_PAD src0_sel:WORD_1
	v_cvt_f32_f16_e32 v56, v28
	v_cvt_f32_f16_sdwa v61, v30 dst_sel:DWORD dst_unused:UNUSED_PAD src0_sel:WORD_1
	s_waitcnt lgkmcnt(0)
	v_cvt_pk_bf16_f32 v33, v34, v35
	global_store_dword v[58:59], v33, off nt
	v_cvt_f32_f16_sdwa v59, v29 dst_sel:DWORD dst_unused:UNUSED_PAD src0_sel:WORD_1
	v_cvt_f32_f16_e32 v58, v29
	v_cvt_f32_f16_e32 v60, v30
	v_cvt_f32_f16_sdwa v63, v31 dst_sel:DWORD dst_unused:UNUSED_PAD src0_sel:WORD_1
	v_cvt_f32_f16_e32 v62, v31
	s_waitcnt vmcnt(8)
	v_cvt_f32_f16_sdwa v33, v24 dst_sel:DWORD dst_unused:UNUSED_PAD src0_sel:WORD_1
	v_cvt_f32_f16_e32 v70, v24
	v_cvt_f32_f16_sdwa v71, v25 dst_sel:DWORD dst_unused:UNUSED_PAD src0_sel:WORD_1
	v_cvt_f32_f16_e32 v72, v25
	v_cvt_f32_f16_sdwa v73, v26 dst_sel:DWORD dst_unused:UNUSED_PAD src0_sel:WORD_1
	v_cvt_f32_f16_e32 v74, v26
	v_cvt_f32_f16_sdwa v75, v27 dst_sel:DWORD dst_unused:UNUSED_PAD src0_sel:WORD_1
	v_cvt_f32_f16_e32 v76, v27
	s_waitcnt vmcnt(7)
	v_cvt_f32_f16_sdwa v25, v20 dst_sel:DWORD dst_unused:UNUSED_PAD src0_sel:WORD_1
	v_cvt_f32_f16_e32 v24, v20
	v_cvt_f32_f16_sdwa v27, v21 dst_sel:DWORD dst_unused:UNUSED_PAD src0_sel:WORD_1
	v_cvt_f32_f16_e32 v26, v21
	v_cvt_f32_f16_sdwa v29, v22 dst_sel:DWORD dst_unused:UNUSED_PAD src0_sel:WORD_1
	v_cvt_f32_f16_e32 v28, v22
	v_cvt_f32_f16_sdwa v31, v23 dst_sel:DWORD dst_unused:UNUSED_PAD src0_sel:WORD_1
	v_cvt_f32_f16_e32 v30, v23
	s_waitcnt vmcnt(6)
	v_cvt_f32_f16_e32 v20, v12
	s_waitcnt vmcnt(3)
	v_cvt_f32_f16_e32 v21, v4
	s_waitcnt vmcnt(2)
	v_cvt_f32_f16_e32 v22, v8
	v_cvt_f32_f16_e32 v23, v16
	v_cvt_f32_f16_sdwa v16, v16 dst_sel:DWORD dst_unused:UNUSED_PAD src0_sel:WORD_1
	v_mul_f32_e32 v34, v20, v21
	v_mul_f32_e32 v35, v20, v22
	v_sub_f32_e32 v21, 1.0, v23
	v_cvt_f32_f16_sdwa v23, v17 dst_sel:DWORD dst_unused:UNUSED_PAD src0_sel:WORD_1
	v_cvt_f32_f16_e32 v22, v17
	v_cvt_f32_f16_sdwa v67, v13 dst_sel:DWORD dst_unused:UNUSED_PAD src0_sel:WORD_1
	v_cvt_f32_f16_e32 v66, v13
	v_cvt_f32_f16_sdwa v12, v12 dst_sel:DWORD dst_unused:UNUSED_PAD src0_sel:WORD_1
	v_cvt_f32_f16_sdwa v64, v4 dst_sel:DWORD dst_unused:UNUSED_PAD src0_sel:WORD_1
	v_cvt_f32_f16_sdwa v65, v8 dst_sel:DWORD dst_unused:UNUSED_PAD src0_sel:WORD_1
	v_sub_f32_e32 v4, 1.0, v16
	v_pk_add_f32 v[16:17], v[22:23], 1.0 op_sel_hi:[1,0] neg_lo:[1,0] neg_hi:[1,0]
	v_mul_f32_e32 v21, v21, v20
	v_pk_mul_f32 v[16:17], v[16:17], v[66:67]
	v_mul_f32_e32 v4, v4, v12
	v_cndmask_b32_e32 v23, v17, v67, vcc
	v_cndmask_b32_e32 v22, v16, v66, vcc
	v_cvt_f32_f16_sdwa v17, v14 dst_sel:DWORD dst_unused:UNUSED_PAD src0_sel:WORD_1
	v_cvt_f32_f16_e32 v16, v14
	v_cvt_f32_f16_sdwa v69, v15 dst_sel:DWORD dst_unused:UNUSED_PAD src0_sel:WORD_1
	v_cvt_f32_f16_e32 v68, v15
	v_pk_add_f32 v[14:15], v[34:35], 0 op_sel_hi:[1,0]
	v_cndmask_b32_e32 v20, v21, v20, vcc
	v_cndmask_b32_e32 v21, v4, v12, vcc
	v_pk_fma_f32 v[12:13], v[12:13], v[64:65], v[14:15] op_sel_hi:[0,1,1]
	v_cvt_f32_f16_e32 v15, v9
	v_cvt_f32_f16_e32 v14, v5
	v_cvt_f32_f16_sdwa v9, v9 dst_sel:DWORD dst_unused:UNUSED_PAD src0_sel:WORD_1
	v_cvt_f32_f16_sdwa v8, v5 dst_sel:DWORD dst_unused:UNUSED_PAD src0_sel:WORD_1
	v_cvt_f32_f16_e32 v5, v10
	v_cvt_f32_f16_e32 v4, v6
	v_pk_fma_f32 v[12:13], v[66:67], v[14:15], v[12:13] op_sel_hi:[0,1,1]
	v_mov_b32_e32 v14, v67
	v_pk_fma_f32 v[8:9], v[14:15], v[8:9], v[12:13] op_sel_hi:[0,1,1]
	v_pk_fma_f32 v[4:5], v[16:17], v[4:5], v[8:9] op_sel_hi:[0,1,1]
	v_cvt_f32_f16_sdwa v9, v10 dst_sel:DWORD dst_unused:UNUSED_PAD src0_sel:WORD_1
	v_cvt_f32_f16_sdwa v8, v6 dst_sel:DWORD dst_unused:UNUSED_PAD src0_sel:WORD_1
	v_cvt_f32_f16_e32 v13, v11
	v_cvt_f32_f16_e32 v12, v7
	v_cvt_f32_f16_sdwa v11, v11 dst_sel:DWORD dst_unused:UNUSED_PAD src0_sel:WORD_1
	v_cvt_f32_f16_sdwa v10, v7 dst_sel:DWORD dst_unused:UNUSED_PAD src0_sel:WORD_1
	s_bitcmp1_b32 s25, 0
	v_cvt_f32_f16_sdwa v77, v18 dst_sel:DWORD dst_unused:UNUSED_PAD src0_sel:WORD_1
	v_cvt_f32_f16_e32 v18, v18
	v_cvt_f32_f16_sdwa v78, v19 dst_sel:DWORD dst_unused:UNUSED_PAD src0_sel:WORD_1
	v_cvt_f32_f16_e32 v19, v19
	v_mov_b32_e32 v6, v17
	s_cselect_b32 s4, 0xa880, 0
	v_pk_fma_f32 v[4:5], v[6:7], v[8:9], v[4:5] op_sel_hi:[0,1,1]
	s_add_i32 s24, s4, 0
	v_pk_fma_f32 v[4:5], v[68:69], v[12:13], v[4:5] op_sel_hi:[0,1,1]
	v_mov_b32_e32 v6, v69
	v_pk_fma_f32 v[4:5], v[6:7], v[10:11], v[4:5] op_sel_hi:[0,1,1]
	v_add_u32_e32 v34, s24, v48
	v_sub_f32_e32 v10, 1.0, v72
	v_sub_f32_e32 v8, 1.0, v70
	v_sub_f32_e32 v11, 1.0, v71
	v_sub_f32_e32 v9, 1.0, v33
	ds_write_b128 v34, v[56:59]
	ds_write_b128 v34, v[60:63] offset:16
	v_sub_f32_e32 v14, 1.0, v76
	v_sub_f32_e32 v12, 1.0, v74
	v_sub_f32_e32 v15, 1.0, v75
	v_sub_f32_e32 v13, 1.0, v73
	ds_write_b128 v34, v[8:11] offset:8192
	ds_write_b128 v34, v[12:15] offset:8208
	ds_write_b128 v34, v[24:27] offset:16384
	ds_write_b128 v34, v[28:31] offset:16400
	v_sub_f32_e32 v8, 1.0, v19
	v_sub_f32_e32 v9, 1.0, v78
	v_sub_f32_e32 v10, 1.0, v18
	v_sub_f32_e32 v11, 1.0, v77
	v_pk_mul_f32 v[12:13], v[10:11], v[16:17]
	v_pk_mul_f32 v[8:9], v[8:9], v[68:69]
	v_mov_b32_dpp v6, v4 quad_perm:[1,0,3,2] row_mask:0xf bank_mask:0xf bound_ctrl:1
	v_mov_b32_dpp v7, v5 quad_perm:[1,0,3,2] row_mask:0xf bank_mask:0xf bound_ctrl:1
	v_cndmask_b32_e32 v11, v9, v69, vcc
	v_cndmask_b32_e32 v10, v8, v68, vcc
	v_cndmask_b32_e32 v9, v13, v17, vcc
	v_cndmask_b32_e32 v8, v12, v16, vcc
	v_pk_add_f32 v[4:5], v[4:5], v[6:7]
	ds_write_b128 v34, v[20:23] offset:24576
	ds_write_b128 v34, v[8:11] offset:24592
	v_cvt_f32_f16_sdwa v11, -v1 dst_sel:DWORD dst_unused:UNUSED_PAD src0_sel:WORD_1
	v_cvt_f32_f16_sdwa v9, -v0 dst_sel:DWORD dst_unused:UNUSED_PAD src0_sel:WORD_1
	v_cvt_f32_f16_e64 v10, -v1
	v_cvt_f32_f16_e64 v8, -v0
	s_waitcnt vmcnt(1)
	v_cvt_f32_f16_sdwa v1, v55 dst_sel:DWORD dst_unused:UNUSED_PAD src0_sel:WORD_1
	v_cvt_f32_f16_e32 v0, v55
	v_mov_b32_dpp v6, v4 quad_perm:[2,3,0,1] row_mask:0xf bank_mask:0xf bound_ctrl:1
	v_mov_b32_dpp v7, v5 quad_perm:[2,3,0,1] row_mask:0xf bank_mask:0xf bound_ctrl:1
	v_cvt_f32_f16_sdwa v15, -v3 dst_sel:DWORD dst_unused:UNUSED_PAD src0_sel:WORD_1
	v_cvt_f32_f16_sdwa v13, -v2 dst_sel:DWORD dst_unused:UNUSED_PAD src0_sel:WORD_1
	v_cvt_f32_f16_e64 v14, -v3
	v_cvt_f32_f16_e64 v12, -v2
	v_pk_add_f32 v[4:5], v[4:5], v[6:7]
	v_add3_u32 v2, s24, v50, v51
	ds_write_b128 v34, v[8:11] offset:32768
	ds_write_b128 v34, v[12:15] offset:32784
	v_mov_b32_dpp v6, v4 row_half_mirror row_mask:0xf bank_mask:0xf bound_ctrl:1
	v_mov_b32_dpp v7, v5 row_half_mirror row_mask:0xf bank_mask:0xf bound_ctrl:1
	ds_write_b64 v2, v[0:1] offset:40960
	s_and_saveexec_b64 s[4:5], s[0:1]
	s_cbranch_execz .LBB0_796
	v_pk_add_f32 v[0:1], v[4:5], v[6:7]
	v_lshl_add_u32 v2, v52, 2, s24
	ds_write_b64 v2, v[0:1] offset:43008
	s_branch .LBB0_796
; __device__ __forceinline__ unsigned pk_bf16(float lo, float hi) { const f32x2 v = {lo, hi}; return __builtin_bit_cast(unsigned, __builtin_convertvector(v, b16x2)); }
; __device__ __forceinline__ void scan_unit(const Params& p, int unit) {
;     ...
;         auto yout = [&](int c) {
;             const float* yb = (const float*)(smem + SC_YOFF + (c & 1) * SC_YBUF);
;             const f32x2 v = *(const f32x2*)(yb + (i >> 3) * 16 + (i & 7) * 2);
;             *(unsigned*)(Y + hb + (size_t)(c * SC_TC + (i >> 3)) * 64 + vr0 + (i & 7) * 2) = pk_bf16(v[0], v[1]);
;         };
;         issue(0); commit(0); issue(1);
;         __syncthreads();
;         for (int c = 0; c < SC_NC; ++c) {
;             if (c > 0) yout(c - 1);
;             if (c + 1 < SC_NC) commit((c + 1) & 1);
;             if (c + 2 < SC_NC) issue(c + 2);
;             __syncthreads();
;         }
.LBB0_799:
	s_add_u32 s4, s90, s21
	ds_read_b64 v[38:39], v54
	s_addc_u32 s5, s91, s20
	s_add_u32 s4, s4, 0x1b588000
	s_addc_u32 s5, s5, 0
	v_mov_b32_e32 v35, 0
	s_add_u32 s6, s4, s10
	s_addc_u32 s7, s5, 0
	v_lshlrev_b32_e32 v34, 1, v49
	s_waitcnt lgkmcnt(0)
	v_cvt_pk_bf16_f32 v33, v38, v39
	v_add_u32_e32 v38, 0x1fc0, v32
	v_mov_b32_e32 v39, v35
	v_lshl_add_u64 v[36:37], s[6:7], 0, v[34:35]
	v_lshlrev_b64 v[38:39], 7, v[38:39]
	v_lshl_add_u64 v[38:39], v[36:37], 0, v[38:39]
	global_store_dword v[38:39], v33, off nt
	s_waitcnt vmcnt(9)
	v_cvt_f32_f16_sdwa v39, v28 dst_sel:DWORD dst_unused:UNUSED_PAD src0_sel:WORD_1
	v_cvt_f32_f16_e32 v38, v28
	v_cvt_f32_f16_sdwa v41, v29 dst_sel:DWORD dst_unused:UNUSED_PAD src0_sel:WORD_1
	v_cvt_f32_f16_e32 v40, v29
	v_cvt_f32_f16_sdwa v43, v30 dst_sel:DWORD dst_unused:UNUSED_PAD src0_sel:WORD_1
	v_cvt_f32_f16_e32 v42, v30
	v_cvt_f32_f16_sdwa v45, v31 dst_sel:DWORD dst_unused:UNUSED_PAD src0_sel:WORD_1
	v_cvt_f32_f16_e32 v44, v31
	s_waitcnt vmcnt(8)
	v_cvt_f32_f16_sdwa v33, v24 dst_sel:DWORD dst_unused:UNUSED_PAD src0_sel:WORD_1
	v_cvt_f32_f16_e32 v52, v24
	v_cvt_f32_f16_sdwa v60, v25 dst_sel:DWORD dst_unused:UNUSED_PAD src0_sel:WORD_1
	v_cvt_f32_f16_e32 v61, v25
	v_cvt_f32_f16_sdwa v62, v26 dst_sel:DWORD dst_unused:UNUSED_PAD src0_sel:WORD_1
	v_cvt_f32_f16_e32 v63, v26
	v_cvt_f32_f16_sdwa v64, v27 dst_sel:DWORD dst_unused:UNUSED_PAD src0_sel:WORD_1
	v_cvt_f32_f16_e32 v65, v27
	s_waitcnt vmcnt(7)
	v_cvt_f32_f16_sdwa v25, v20 dst_sel:DWORD dst_unused:UNUSED_PAD src0_sel:WORD_1
	v_cvt_f32_f16_e32 v24, v20
	v_cvt_f32_f16_sdwa v27, v21 dst_sel:DWORD dst_unused:UNUSED_PAD src0_sel:WORD_1
	v_cvt_f32_f16_e32 v26, v21
	v_cvt_f32_f16_sdwa v29, v22 dst_sel:DWORD dst_unused:UNUSED_PAD src0_sel:WORD_1
	v_cvt_f32_f16_e32 v28, v22
	v_cvt_f32_f16_sdwa v31, v23 dst_sel:DWORD dst_unused:UNUSED_PAD src0_sel:WORD_1
	v_cvt_f32_f16_e32 v30, v23
	s_waitcnt vmcnt(6)
	v_cvt_f32_f16_e32 v20, v12
	s_waitcnt vmcnt(3)
	v_cvt_f32_f16_e32 v21, v4
	s_waitcnt vmcnt(2)
	v_cvt_f32_f16_e32 v22, v8
	v_cvt_f32_f16_e32 v23, v16
	v_cvt_f32_f16_sdwa v16, v16 dst_sel:DWORD dst_unused:UNUSED_PAD src0_sel:WORD_1
	v_mul_f32_e32 v48, v20, v21
	v_mul_f32_e32 v49, v20, v22
	v_sub_f32_e32 v21, 1.0, v23
	v_cvt_f32_f16_sdwa v23, v17 dst_sel:DWORD dst_unused:UNUSED_PAD src0_sel:WORD_1
	v_cvt_f32_f16_e32 v22, v17
	v_cvt_f32_f16_sdwa v57, v13 dst_sel:DWORD dst_unused:UNUSED_PAD src0_sel:WORD_1
	v_cvt_f32_f16_e32 v56, v13
	v_cvt_f32_f16_sdwa v12, v12 dst_sel:DWORD dst_unused:UNUSED_PAD src0_sel:WORD_1
	v_cvt_f32_f16_sdwa v50, v4 dst_sel:DWORD dst_unused:UNUSED_PAD src0_sel:WORD_1
	v_cvt_f32_f16_sdwa v51, v8 dst_sel:DWORD dst_unused:UNUSED_PAD src0_sel:WORD_1
	v_sub_f32_e32 v4, 1.0, v16
	v_pk_add_f32 v[16:17], v[22:23], 1.0 op_sel_hi:[1,0] neg_lo:[1,0] neg_hi:[1,0]
	v_mul_f32_e32 v21, v21, v20
	v_pk_mul_f32 v[16:17], v[16:17], v[56:57]
	v_mul_f32_e32 v4, v4, v12
	v_cndmask_b32_e32 v23, v17, v57, vcc
	v_cndmask_b32_e32 v22, v16, v56, vcc
	v_cvt_f32_f16_sdwa v17, v14 dst_sel:DWORD dst_unused:UNUSED_PAD src0_sel:WORD_1
	v_cvt_f32_f16_e32 v16, v14
	v_cvt_f32_f16_sdwa v59, v15 dst_sel:DWORD dst_unused:UNUSED_PAD src0_sel:WORD_1
	v_cvt_f32_f16_e32 v58, v15
	v_pk_add_f32 v[14:15], v[48:49], 0 op_sel_hi:[1,0]
	v_cndmask_b32_e32 v20, v21, v20, vcc
	v_cndmask_b32_e32 v21, v4, v12, vcc
	v_pk_fma_f32 v[12:13], v[12:13], v[50:51], v[14:15] op_sel_hi:[0,1,1]
	v_cvt_f32_f16_e32 v15, v9
	v_cvt_f32_f16_e32 v14, v5
	v_cvt_f32_f16_sdwa v9, v9 dst_sel:DWORD dst_unused:UNUSED_PAD src0_sel:WORD_1
	v_cvt_f32_f16_sdwa v8, v5 dst_sel:DWORD dst_unused:UNUSED_PAD src0_sel:WORD_1
	v_cvt_f32_f16_e32 v5, v10
	v_cvt_f32_f16_e32 v4, v6
	v_pk_fma_f32 v[12:13], v[56:57], v[14:15], v[12:13] op_sel_hi:[0,1,1]
	v_mov_b32_e32 v14, v57
	v_pk_fma_f32 v[8:9], v[14:15], v[8:9], v[12:13] op_sel_hi:[0,1,1]
	v_pk_fma_f32 v[4:5], v[16:17], v[4:5], v[8:9] op_sel_hi:[0,1,1]
	v_cvt_f32_f16_sdwa v9, v10 dst_sel:DWORD dst_unused:UNUSED_PAD src0_sel:WORD_1
	v_cvt_f32_f16_sdwa v8, v6 dst_sel:DWORD dst_unused:UNUSED_PAD src0_sel:WORD_1
	v_cvt_f32_f16_e32 v13, v11
	v_cvt_f32_f16_e32 v12, v7
	v_cvt_f32_f16_sdwa v11, v11 dst_sel:DWORD dst_unused:UNUSED_PAD src0_sel:WORD_1
	v_cvt_f32_f16_sdwa v10, v7 dst_sel:DWORD dst_unused:UNUSED_PAD src0_sel:WORD_1
	v_cvt_f32_f16_sdwa v66, v18 dst_sel:DWORD dst_unused:UNUSED_PAD src0_sel:WORD_1
	v_cvt_f32_f16_e32 v18, v18
	v_cvt_f32_f16_sdwa v67, v19 dst_sel:DWORD dst_unused:UNUSED_PAD src0_sel:WORD_1
	v_cvt_f32_f16_e32 v19, v19
	v_mov_b32_e32 v6, v17
	v_pk_fma_f32 v[4:5], v[6:7], v[8:9], v[4:5] op_sel_hi:[0,1,1]
	v_pk_fma_f32 v[4:5], v[58:59], v[12:13], v[4:5] op_sel_hi:[0,1,1]
	v_mov_b32_e32 v6, v59
	v_pk_fma_f32 v[4:5], v[6:7], v[10:11], v[4:5] op_sel_hi:[0,1,1]
	v_sub_f32_e32 v10, 1.0, v61
	v_sub_f32_e32 v8, 1.0, v52
	v_sub_f32_e32 v11, 1.0, v60
	v_sub_f32_e32 v9, 1.0, v33
	v_mov_b32_dpp v6, v4 quad_perm:[1,0,3,2] row_mask:0xf bank_mask:0xf bound_ctrl:1
	v_mov_b32_dpp v7, v5 quad_perm:[1,0,3,2] row_mask:0xf bank_mask:0xf bound_ctrl:1
	ds_write_b128 v46, v[38:41]
	ds_write_b128 v46, v[42:45] offset:16
	v_sub_f32_e32 v14, 1.0, v65
	v_sub_f32_e32 v12, 1.0, v63
	v_sub_f32_e32 v15, 1.0, v64
	v_sub_f32_e32 v13, 1.0, v62
	ds_write_b128 v46, v[8:11] offset:8192
	ds_write_b128 v46, v[12:15] offset:8208
	ds_write_b128 v46, v[24:27] offset:16384
	ds_write_b128 v46, v[28:31] offset:16400
	v_sub_f32_e32 v8, 1.0, v19
	v_sub_f32_e32 v9, 1.0, v67
	v_sub_f32_e32 v10, 1.0, v18
	v_sub_f32_e32 v11, 1.0, v66
	v_pk_add_f32 v[4:5], v[4:5], v[6:7]
	v_pk_mul_f32 v[12:13], v[10:11], v[16:17]
	v_pk_mul_f32 v[8:9], v[8:9], v[58:59]
	v_mov_b32_dpp v6, v4 quad_perm:[2,3,0,1] row_mask:0xf bank_mask:0xf bound_ctrl:1
	v_mov_b32_dpp v7, v5 quad_perm:[2,3,0,1] row_mask:0xf bank_mask:0xf bound_ctrl:1
	v_cndmask_b32_e32 v11, v9, v59, vcc
	v_cndmask_b32_e32 v10, v8, v58, vcc
	v_cndmask_b32_e32 v9, v13, v17, vcc
	v_cndmask_b32_e32 v8, v12, v16, vcc
	v_cvt_f32_f16_sdwa v15, -v1 dst_sel:DWORD dst_unused:UNUSED_PAD src0_sel:WORD_1
	v_cvt_f32_f16_sdwa v13, -v0 dst_sel:DWORD dst_unused:UNUSED_PAD src0_sel:WORD_1
	v_cvt_f32_f16_e64 v14, -v1
	v_cvt_f32_f16_e64 v12, -v0
	v_pk_add_f32 v[4:5], v[4:5], v[6:7]
	v_cvt_f32_f16_sdwa v19, -v3 dst_sel:DWORD dst_unused:UNUSED_PAD src0_sel:WORD_1
	v_cvt_f32_f16_sdwa v17, -v2 dst_sel:DWORD dst_unused:UNUSED_PAD src0_sel:WORD_1
	v_cvt_f32_f16_e64 v18, -v3
	v_cvt_f32_f16_e64 v16, -v2
	s_mov_b32 s11, 0
	v_mov_b32_dpp v6, v4 row_half_mirror row_mask:0xf bank_mask:0xf bound_ctrl:1
	v_mov_b32_dpp v7, v5 row_half_mirror row_mask:0xf bank_mask:0xf bound_ctrl:1
	s_waitcnt vmcnt(1)
	v_cvt_f32_f16_sdwa v1, v55 dst_sel:DWORD dst_unused:UNUSED_PAD src0_sel:WORD_1
	v_cvt_f32_f16_e32 v0, v55
	ds_write_b128 v46, v[20:23] offset:24576
	ds_write_b128 v46, v[8:11] offset:24592
	ds_write_b128 v46, v[12:15] offset:32768
	ds_write_b128 v46, v[16:19] offset:32784
	ds_write_b64 v47, v[0:1] offset:40960
	s_and_saveexec_b64 s[6:7], s[0:1]
	v_pk_add_f32 v[0:1], v[4:5], v[6:7]
	ds_write_b64 v53, v[0:1] offset:43008
	s_or_b64 exec, exec, s[6:7]
	s_waitcnt lgkmcnt(0)
	s_barrier
; __device__ __forceinline__ unsigned pk_bf16(float lo, float hi) { const f32x2 v = {lo, hi}; return __builtin_bit_cast(unsigned, __builtin_convertvector(v, b16x2)); }
; __device__ __forceinline__ void scan_unit(const Params& p, int unit) {
;     ...
;         auto yout = [&](int c) {
;             const float* yb = (const float*)(smem + SC_YOFF + (c & 1) * SC_YBUF);
;             const f32x2 v = *(const f32x2*)(yb + (i >> 3) * 16 + (i & 7) * 2);
;             *(unsigned*)(Y + hb + (size_t)(c * SC_TC + (i >> 3)) * 64 + vr0 + (i & 7) * 2) = pk_bf16(v[0], v[1]);
;         };
;         issue(0); commit(0); issue(1);
;         __syncthreads();
;         for (int c = 0; c < SC_NC; ++c) {
;             if (c > 0) yout(c - 1);
;             if (c + 1 < SC_NC) commit((c + 1) & 1);
;             if (c + 2 < SC_NC) issue(c + 2);
;             __syncthreads();
;         }
;         yout(SC_NC - 1);
	ds_read_b64 v[0:1], v54 offset:2048
	v_add_u32_e32 v2, 0x1fe0, v32
	v_mov_b32_e32 v3, v35
	s_waitcnt lgkmcnt(0)
	v_cvt_pk_bf16_f32 v4, v0, v1
	v_lshlrev_b64 v[0:1], 7, v[2:3]
	v_lshl_add_u64 v[0:1], v[36:37], 0, v[0:1]
	global_store_dword v[0:1], v4, off nt
	s_barrier
	ds_read_b64 v[0:1], v54
	s_waitcnt lgkmcnt(0)
	v_cvt_pk_bf16_f32 v2, v0, v1
	v_add_u32_e32 v0, 0x2000, v32
	v_mov_b32_e32 v1, v35
	v_lshlrev_b64 v[0:1], 7, v[0:1]
	v_lshl_add_u64 v[0:1], s[4:5], 0, v[0:1]
	v_lshl_add_u64 v[0:1], v[0:1], 0, s[10:11]
	v_lshl_add_u64 v[0:1], v[0:1], 0, v[34:35]
	global_store_dword v[0:1], v2, off nt
